# K-loop first load segment: 16 ds_reads issued before the pointer/counter SALU block (and before tile-init SALU in the peeled iteration)
# speedup vs baseline: 1.0135x; 1.0135x over previous
.Lprio_done:
	s_add_i32 s83, 0, 0x10000
	s_add_i32 s82, 0, 0x14000
	v_add_u32_e32 v140, s83, v157
	v_add_u32_e32 v144, s82, v157
	ds_read_b128 v[128:131], v140
	ds_read_b128 v[132:135], v140 offset:1024
	ds_read_b128 v[136:139], v140 offset:2048
	ds_read_b128 v[140:143], v140 offset:3072
	ds_read_b128 v[166:169], v144
	ds_read_b128 v[176:179], v144 offset:1024
	ds_read_b128 v[180:183], v144 offset:2048
	ds_read_b128 v[184:187], v144 offset:3072
	ds_read_b128 v[188:191], v242
	ds_read_b128 v[192:195], v242 offset:1024
	ds_read_b128 v[196:199], v242 offset:2048
	ds_read_b128 v[200:203], v242 offset:3072
	ds_read_b128 v[204:207], v242 offset:4096
	ds_read_b128 v[208:211], v242 offset:5120
	ds_read_b128 v[212:215], v242 offset:6144
	ds_read_b128 v[216:219], v242 offset:7168
	s_add_u32 s0, s90, 0x80
	s_addc_u32 s1, s91, 0
	s_add_u32 s11, s2, 0x100
	s_addc_u32 s24, s3, 0
	s_mov_b32 s2, 0
	s_add_i32 s90, s2, 2
	s_add_u32 s82, s0, 0x80
	s_addc_u32 s3, s1, 0
	s_add_i32 s83, 0, 0x10000
	s_cmp_eq_u32 s62, s2
	s_cselect_b32 s3, s23, s3
	s_cselect_b32 s2, s22, s82
	s_cselect_b32 vcc_hi, s13, s24
	s_cselect_b32 vcc_lo, s12, s11
	s_add_i32 s82, 0, 0x14000
	s_add_i32 m0, s37, 0xc000
	v_lshl_add_u64 v[170:171], s[0:1], 0, v[160:161]
	global_load_lds_dwordx4 v[170:171], off
	v_lshl_add_u64 v[170:171], s[0:1], 0, v[162:163]
	s_add_i32 m0, s37, 0xe000
	s_nop 0
	global_load_lds_dwordx4 v[170:171], off
	s_waitcnt vmcnt(8) lgkmcnt(0)
	s_barrier
	v_mfma_f32_16x16x32_bf16 v[124:127], v[128:131], v[188:191], 0
	v_mfma_f32_16x16x32_bf16 v[120:123], v[136:139], v[188:191], 0
	v_mfma_f32_16x16x32_bf16 v[108:111], v[128:131], v[196:199], 0
	v_mfma_f32_16x16x32_bf16 v[104:107], v[136:139], v[196:199], 0
	v_mfma_f32_16x16x32_bf16 v[92:95], v[128:131], v[204:207], 0
	v_mfma_f32_16x16x32_bf16 v[88:91], v[136:139], v[204:207], 0
	v_mfma_f32_16x16x32_bf16 v[76:79], v[128:131], v[212:215], 0
	v_mfma_f32_16x16x32_bf16 v[72:75], v[136:139], v[212:215], 0
	v_mfma_f32_16x16x32_bf16 v[124:127], v[132:135], v[192:195], v[124:127]
	v_mfma_f32_16x16x32_bf16 v[120:123], v[140:143], v[192:195], v[120:123]
	v_mfma_f32_16x16x32_bf16 v[108:111], v[132:135], v[200:203], v[108:111]
	v_mfma_f32_16x16x32_bf16 v[104:107], v[140:143], v[200:203], v[104:107]
	v_mfma_f32_16x16x32_bf16 v[92:95], v[132:135], v[208:211], v[92:95]
	v_mfma_f32_16x16x32_bf16 v[88:91], v[140:143], v[208:211], v[88:91]
	v_mfma_f32_16x16x32_bf16 v[76:79], v[132:135], v[216:219], v[76:79]
	v_mfma_f32_16x16x32_bf16 v[72:75], v[140:143], v[216:219], v[72:75]
	v_mfma_f32_16x16x32_bf16 v[116:119], v[166:169], v[188:191], 0
	v_mfma_f32_16x16x32_bf16 v[112:115], v[180:183], v[188:191], 0
	v_mfma_f32_16x16x32_bf16 v[100:103], v[166:169], v[196:199], 0
	v_mfma_f32_16x16x32_bf16 v[96:99], v[180:183], v[196:199], 0
	v_mfma_f32_16x16x32_bf16 v[84:87], v[166:169], v[204:207], 0
	v_mfma_f32_16x16x32_bf16 v[80:83], v[180:183], v[204:207], 0
	v_mfma_f32_16x16x32_bf16 v[68:71], v[166:169], v[212:215], 0
	v_mfma_f32_16x16x32_bf16 v[64:67], v[180:183], v[212:215], 0
	v_mfma_f32_16x16x32_bf16 v[116:119], v[176:179], v[192:195], v[116:119]
	v_mfma_f32_16x16x32_bf16 v[112:115], v[184:187], v[192:195], v[112:115]
	v_mfma_f32_16x16x32_bf16 v[100:103], v[176:179], v[200:203], v[100:103]
	v_mfma_f32_16x16x32_bf16 v[96:99], v[184:187], v[200:203], v[96:99]
	v_mfma_f32_16x16x32_bf16 v[84:87], v[176:179], v[208:211], v[84:87]
	v_mfma_f32_16x16x32_bf16 v[80:83], v[184:187], v[208:211], v[80:83]
	v_mfma_f32_16x16x32_bf16 v[68:71], v[176:179], v[216:219], v[68:71]
	v_mfma_f32_16x16x32_bf16 v[64:67], v[184:187], v[216:219], v[64:67]
	s_barrier
	s_add_i32 s83, s83, s36
	v_lshl_add_u64 v[170:171], vcc, 0, v[150:151]
	s_mov_b32 m0, s83
	ds_read_b128 v[188:191], v242 offset:16384
	ds_read_b128 v[192:195], v242 offset:17408
	ds_read_b128 v[196:199], v242 offset:18432
	ds_read_b128 v[200:203], v242 offset:19456
	ds_read_b128 v[204:207], v242 offset:20480
	ds_read_b128 v[208:211], v242 offset:21504
	ds_read_b128 v[212:215], v242 offset:22528
	ds_read_b128 v[216:219], v242 offset:23552
	global_load_lds_dwordx4 v[170:171], off
	s_add_i32 m0, s83, 0x2000
	v_lshl_add_u64 v[232:233], vcc, 0, v[154:155]
	s_add_u32 vcc_lo, vcc_lo, s26
	s_addc_u32 vcc_hi, vcc_hi, 0
	s_add_i32 s82, s82, s36
	global_load_lds_dwordx4 v[232:233], off
	v_lshl_add_u64 v[234:235], vcc, 0, v[150:151]
	s_mov_b32 m0, s82
	v_lshl_add_u64 v[246:247], vcc, 0, v[154:155]
	global_load_lds_dwordx4 v[234:235], off
	s_add_i32 m0, s82, 0x2000
	v_lshl_add_u64 v[248:249], s[2:3], 0, v[148:149]
	global_load_lds_dwordx4 v[246:247], off
	s_mov_b32 m0, s37
	v_lshl_add_u64 v[250:251], s[2:3], 0, v[152:153]
	global_load_lds_dwordx4 v[248:249], off
	s_mov_b32 m0, s42
	s_nop 0
	global_load_lds_dwordx4 v[250:251], off
	s_waitcnt vmcnt(8) lgkmcnt(0)
	s_barrier
	v_mfma_f32_16x16x32_bf16 v[60:63], v[128:131], v[188:191], 0
	v_mfma_f32_16x16x32_bf16 v[56:59], v[136:139], v[188:191], 0
	v_mfma_f32_16x16x32_bf16 v[44:47], v[128:131], v[196:199], 0
	v_mfma_f32_16x16x32_bf16 v[40:43], v[136:139], v[196:199], 0
	v_mfma_f32_16x16x32_bf16 v[28:31], v[128:131], v[204:207], 0
	v_mfma_f32_16x16x32_bf16 v[24:27], v[136:139], v[204:207], 0
	v_mfma_f32_16x16x32_bf16 v[12:15], v[128:131], v[212:215], 0
	v_mfma_f32_16x16x32_bf16 v[8:11], v[136:139], v[212:215], 0
	v_mfma_f32_16x16x32_bf16 v[60:63], v[132:135], v[192:195], v[60:63]
	v_mfma_f32_16x16x32_bf16 v[56:59], v[140:143], v[192:195], v[56:59]
	v_mfma_f32_16x16x32_bf16 v[44:47], v[132:135], v[200:203], v[44:47]
	v_mfma_f32_16x16x32_bf16 v[40:43], v[140:143], v[200:203], v[40:43]
	v_mfma_f32_16x16x32_bf16 v[28:31], v[132:135], v[208:211], v[28:31]
	v_mfma_f32_16x16x32_bf16 v[24:27], v[140:143], v[208:211], v[24:27]
	v_mfma_f32_16x16x32_bf16 v[12:15], v[132:135], v[216:219], v[12:15]
	v_mfma_f32_16x16x32_bf16 v[8:11], v[140:143], v[216:219], v[8:11]
	v_mfma_f32_16x16x32_bf16 v[52:55], v[166:169], v[188:191], 0
	v_mfma_f32_16x16x32_bf16 v[48:51], v[180:183], v[188:191], 0
	v_mfma_f32_16x16x32_bf16 v[36:39], v[166:169], v[196:199], 0
	v_mfma_f32_16x16x32_bf16 v[32:35], v[180:183], v[196:199], 0
	v_mfma_f32_16x16x32_bf16 v[20:23], v[166:169], v[204:207], 0
	v_mfma_f32_16x16x32_bf16 v[16:19], v[180:183], v[204:207], 0
	v_mfma_f32_16x16x32_bf16 v[4:7], v[166:169], v[212:215], 0
	v_mfma_f32_16x16x32_bf16 v[0:3], v[180:183], v[212:215], 0
	v_mfma_f32_16x16x32_bf16 v[52:55], v[176:179], v[192:195], v[52:55]
	v_mfma_f32_16x16x32_bf16 v[48:51], v[184:187], v[192:195], v[48:51]
	v_mfma_f32_16x16x32_bf16 v[36:39], v[176:179], v[200:203], v[36:39]
	v_mfma_f32_16x16x32_bf16 v[32:35], v[184:187], v[200:203], v[32:35]
	v_mfma_f32_16x16x32_bf16 v[20:23], v[176:179], v[208:211], v[20:23]
	v_mfma_f32_16x16x32_bf16 v[16:19], v[184:187], v[208:211], v[16:19]
	v_mfma_f32_16x16x32_bf16 v[4:7], v[176:179], v[216:219], v[4:7]
	v_mfma_f32_16x16x32_bf16 v[0:3], v[184:187], v[216:219], v[0:3]
	s_barrier
	s_add_i32 s82, 0, 0x18000
	s_add_i32 s83, 0, 0x1c000
	v_add_u32_e32 v140, s82, v157
	v_add_u32_e32 v144, s83, v157
	ds_read_b128 v[128:131], v140
	ds_read_b128 v[132:135], v140 offset:1024
	ds_read_b128 v[136:139], v140 offset:2048
	ds_read_b128 v[140:143], v140 offset:3072
	ds_read_b128 v[166:169], v144
	ds_read_b128 v[176:179], v144 offset:1024
	ds_read_b128 v[180:183], v144 offset:2048
	ds_read_b128 v[184:187], v144 offset:3072
	s_add_u32 s2, s2, s58
	s_addc_u32 s3, s3, 0
	s_mov_b32 m0, s43
	v_lshl_add_u64 v[238:239], s[2:3], 0, v[148:149]
	ds_read_b128 v[188:191], v242 offset:32768
	ds_read_b128 v[192:195], v242 offset:33792
	ds_read_b128 v[196:199], v242 offset:34816
	ds_read_b128 v[200:203], v242 offset:35840
	ds_read_b128 v[204:207], v242 offset:36864
	ds_read_b128 v[208:211], v242 offset:37888
	ds_read_b128 v[212:215], v242 offset:38912
	ds_read_b128 v[216:219], v242 offset:39936
	global_load_lds_dwordx4 v[238:239], off
	v_lshl_add_u64 v[238:239], s[2:3], 0, v[152:153]
	s_mov_b32 m0, s16
	s_nop 0
	global_load_lds_dwordx4 v[238:239], off
	s_waitcnt vmcnt(8) lgkmcnt(0)
	s_barrier
	v_mfma_f32_16x16x32_bf16 v[124:127], v[128:131], v[188:191], v[124:127]
	v_mfma_f32_16x16x32_bf16 v[120:123], v[136:139], v[188:191], v[120:123]
	v_mfma_f32_16x16x32_bf16 v[108:111], v[128:131], v[196:199], v[108:111]
	v_mfma_f32_16x16x32_bf16 v[104:107], v[136:139], v[196:199], v[104:107]
	v_mfma_f32_16x16x32_bf16 v[92:95], v[128:131], v[204:207], v[92:95]
	v_mfma_f32_16x16x32_bf16 v[88:91], v[136:139], v[204:207], v[88:91]
	v_mfma_f32_16x16x32_bf16 v[76:79], v[128:131], v[212:215], v[76:79]
	v_mfma_f32_16x16x32_bf16 v[72:75], v[136:139], v[212:215], v[72:75]
	v_mfma_f32_16x16x32_bf16 v[124:127], v[132:135], v[192:195], v[124:127]
	v_mfma_f32_16x16x32_bf16 v[120:123], v[140:143], v[192:195], v[120:123]
	v_mfma_f32_16x16x32_bf16 v[108:111], v[132:135], v[200:203], v[108:111]
	v_mfma_f32_16x16x32_bf16 v[104:107], v[140:143], v[200:203], v[104:107]
	v_mfma_f32_16x16x32_bf16 v[92:95], v[132:135], v[208:211], v[92:95]
	v_mfma_f32_16x16x32_bf16 v[88:91], v[140:143], v[208:211], v[88:91]
	v_mfma_f32_16x16x32_bf16 v[76:79], v[132:135], v[216:219], v[76:79]
	v_mfma_f32_16x16x32_bf16 v[72:75], v[140:143], v[216:219], v[72:75]
	v_mfma_f32_16x16x32_bf16 v[116:119], v[166:169], v[188:191], v[116:119]
	v_mfma_f32_16x16x32_bf16 v[112:115], v[180:183], v[188:191], v[112:115]
	v_mfma_f32_16x16x32_bf16 v[100:103], v[166:169], v[196:199], v[100:103]
	v_mfma_f32_16x16x32_bf16 v[96:99], v[180:183], v[196:199], v[96:99]
	v_mfma_f32_16x16x32_bf16 v[84:87], v[166:169], v[204:207], v[84:87]
	v_mfma_f32_16x16x32_bf16 v[80:83], v[180:183], v[204:207], v[80:83]
	v_mfma_f32_16x16x32_bf16 v[68:71], v[166:169], v[212:215], v[68:71]
	v_mfma_f32_16x16x32_bf16 v[64:67], v[180:183], v[212:215], v[64:67]
	v_mfma_f32_16x16x32_bf16 v[116:119], v[176:179], v[192:195], v[116:119]
	v_mfma_f32_16x16x32_bf16 v[112:115], v[184:187], v[192:195], v[112:115]
	v_mfma_f32_16x16x32_bf16 v[100:103], v[176:179], v[200:203], v[100:103]
	v_mfma_f32_16x16x32_bf16 v[96:99], v[184:187], v[200:203], v[96:99]
	v_mfma_f32_16x16x32_bf16 v[84:87], v[176:179], v[208:211], v[84:87]
	v_mfma_f32_16x16x32_bf16 v[80:83], v[184:187], v[208:211], v[80:83]
	v_mfma_f32_16x16x32_bf16 v[68:71], v[176:179], v[216:219], v[68:71]
	v_mfma_f32_16x16x32_bf16 v[64:67], v[184:187], v[216:219], v[64:67]
	s_barrier
	s_add_i32 s2, s82, s36
	v_lshl_add_u64 v[170:171], v[170:171], 0, s[30:31]
	s_mov_b32 m0, s2
	ds_read_b128 v[188:191], v242 offset:49152
	ds_read_b128 v[192:195], v242 offset:50176
	ds_read_b128 v[196:199], v242 offset:51200
	ds_read_b128 v[200:203], v242 offset:52224
	ds_read_b128 v[204:207], v242 offset:53248
	ds_read_b128 v[208:211], v242 offset:54272
	ds_read_b128 v[212:215], v242 offset:55296
	ds_read_b128 v[216:219], v242 offset:56320
	global_load_lds_dwordx4 v[170:171], off
	v_lshl_add_u64 v[170:171], v[232:233], 0, s[30:31]
	s_add_i32 m0, s2, 0x2000
	s_add_i32 s2, s83, s36
	global_load_lds_dwordx4 v[170:171], off
	v_lshl_add_u64 v[170:171], v[234:235], 0, s[30:31]
	s_mov_b32 m0, s2
	s_nop 0
	global_load_lds_dwordx4 v[170:171], off
	v_lshl_add_u64 v[170:171], v[246:247], 0, s[30:31]
	s_add_i32 m0, s2, 0x2000
	s_nop 0
	global_load_lds_dwordx4 v[170:171], off
	v_lshl_add_u64 v[170:171], v[248:249], 0, s[30:31]
	s_mov_b32 m0, s63
	s_nop 0
	global_load_lds_dwordx4 v[170:171], off
	v_lshl_add_u64 v[170:171], v[250:251], 0, s[30:31]
	s_mov_b32 m0, s18
	s_nop 0
	global_load_lds_dwordx4 v[170:171], off
	s_waitcnt vmcnt(8) lgkmcnt(0)
	s_barrier
	v_mfma_f32_16x16x32_bf16 v[60:63], v[128:131], v[188:191], v[60:63]
	v_mfma_f32_16x16x32_bf16 v[56:59], v[136:139], v[188:191], v[56:59]
	v_mfma_f32_16x16x32_bf16 v[44:47], v[128:131], v[196:199], v[44:47]
	v_mfma_f32_16x16x32_bf16 v[40:43], v[136:139], v[196:199], v[40:43]
	v_mfma_f32_16x16x32_bf16 v[28:31], v[128:131], v[204:207], v[28:31]
	v_mfma_f32_16x16x32_bf16 v[24:27], v[136:139], v[204:207], v[24:27]
	v_mfma_f32_16x16x32_bf16 v[12:15], v[128:131], v[212:215], v[12:15]
	v_mfma_f32_16x16x32_bf16 v[8:11], v[136:139], v[212:215], v[8:11]
	v_mfma_f32_16x16x32_bf16 v[60:63], v[132:135], v[192:195], v[60:63]
	v_mfma_f32_16x16x32_bf16 v[56:59], v[140:143], v[192:195], v[56:59]
	v_mfma_f32_16x16x32_bf16 v[44:47], v[132:135], v[200:203], v[44:47]
	v_mfma_f32_16x16x32_bf16 v[40:43], v[140:143], v[200:203], v[40:43]
	v_mfma_f32_16x16x32_bf16 v[28:31], v[132:135], v[208:211], v[28:31]
	v_mfma_f32_16x16x32_bf16 v[24:27], v[140:143], v[208:211], v[24:27]
	v_mfma_f32_16x16x32_bf16 v[12:15], v[132:135], v[216:219], v[12:15]
	v_mfma_f32_16x16x32_bf16 v[8:11], v[140:143], v[216:219], v[8:11]
	v_mfma_f32_16x16x32_bf16 v[52:55], v[166:169], v[188:191], v[52:55]
	v_mfma_f32_16x16x32_bf16 v[48:51], v[180:183], v[188:191], v[48:51]
	v_mfma_f32_16x16x32_bf16 v[36:39], v[166:169], v[196:199], v[36:39]
	v_mfma_f32_16x16x32_bf16 v[32:35], v[180:183], v[196:199], v[32:35]
	v_mfma_f32_16x16x32_bf16 v[20:23], v[166:169], v[204:207], v[20:23]
	v_mfma_f32_16x16x32_bf16 v[16:19], v[180:183], v[204:207], v[16:19]
	v_mfma_f32_16x16x32_bf16 v[4:7], v[166:169], v[212:215], v[4:7]
	v_mfma_f32_16x16x32_bf16 v[0:3], v[180:183], v[212:215], v[0:3]
	v_mfma_f32_16x16x32_bf16 v[52:55], v[176:179], v[192:195], v[52:55]
	v_mfma_f32_16x16x32_bf16 v[48:51], v[184:187], v[192:195], v[48:51]
	v_mfma_f32_16x16x32_bf16 v[36:39], v[176:179], v[200:203], v[36:39]
	v_mfma_f32_16x16x32_bf16 v[32:35], v[184:187], v[200:203], v[32:35]
	v_mfma_f32_16x16x32_bf16 v[20:23], v[176:179], v[208:211], v[20:23]
	v_mfma_f32_16x16x32_bf16 v[16:19], v[184:187], v[208:211], v[16:19]
	v_mfma_f32_16x16x32_bf16 v[4:7], v[176:179], v[216:219], v[4:7]
	v_mfma_f32_16x16x32_bf16 v[0:3], v[184:187], v[216:219], v[0:3]
	s_barrier
	s_add_u32 s0, s0, 0x100
	s_addc_u32 s1, s1, 0
	s_add_u32 s11, s11, 0x100
	s_addc_u32 s24, s24, 0
	s_cmp_ge_u32 s90, s60
	s_mov_b32 s2, s90
	s_cbranch_scc1 .LBB0_297
.LBB0_295:
	s_add_i32 s83, 0, 0x10000
	s_add_i32 s82, 0, 0x14000
	v_add_u32_e32 v140, s83, v157
	v_add_u32_e32 v144, s82, v157
	ds_read_b128 v[128:131], v140
	ds_read_b128 v[132:135], v140 offset:1024
	ds_read_b128 v[136:139], v140 offset:2048
	ds_read_b128 v[140:143], v140 offset:3072
	ds_read_b128 v[166:169], v144
	ds_read_b128 v[176:179], v144 offset:1024
	ds_read_b128 v[180:183], v144 offset:2048
	ds_read_b128 v[184:187], v144 offset:3072
	ds_read_b128 v[188:191], v242
	ds_read_b128 v[192:195], v242 offset:1024
	ds_read_b128 v[196:199], v242 offset:2048
	ds_read_b128 v[200:203], v242 offset:3072
	ds_read_b128 v[204:207], v242 offset:4096
	ds_read_b128 v[208:211], v242 offset:5120
	ds_read_b128 v[212:215], v242 offset:6144
	ds_read_b128 v[216:219], v242 offset:7168
	s_add_i32 s90, s2, 2
	s_add_u32 s82, s0, 0x80
	s_addc_u32 s3, s1, 0
	s_add_i32 s83, 0, 0x10000
	s_cmp_eq_u32 s62, s2
	s_cselect_b32 s3, s23, s3
	s_cselect_b32 s2, s22, s82
	s_cselect_b32 vcc_hi, s13, s24
	s_cselect_b32 vcc_lo, s12, s11
	s_add_i32 s82, 0, 0x14000
	s_add_i32 m0, s37, 0xc000
	v_lshl_add_u64 v[170:171], s[0:1], 0, v[160:161]
	global_load_lds_dwordx4 v[170:171], off
	v_lshl_add_u64 v[170:171], s[0:1], 0, v[162:163]
	s_add_i32 m0, s37, 0xe000
	s_nop 0
	global_load_lds_dwordx4 v[170:171], off
	s_waitcnt vmcnt(8) lgkmcnt(0)
	s_barrier
	v_mfma_f32_16x16x32_bf16 v[124:127], v[128:131], v[188:191], v[124:127]
	v_mfma_f32_16x16x32_bf16 v[120:123], v[136:139], v[188:191], v[120:123]
	v_mfma_f32_16x16x32_bf16 v[108:111], v[128:131], v[196:199], v[108:111]
	v_mfma_f32_16x16x32_bf16 v[104:107], v[136:139], v[196:199], v[104:107]
	v_mfma_f32_16x16x32_bf16 v[92:95], v[128:131], v[204:207], v[92:95]
	v_mfma_f32_16x16x32_bf16 v[88:91], v[136:139], v[204:207], v[88:91]
	v_mfma_f32_16x16x32_bf16 v[76:79], v[128:131], v[212:215], v[76:79]
	v_mfma_f32_16x16x32_bf16 v[72:75], v[136:139], v[212:215], v[72:75]
	v_mfma_f32_16x16x32_bf16 v[124:127], v[132:135], v[192:195], v[124:127]
	v_mfma_f32_16x16x32_bf16 v[120:123], v[140:143], v[192:195], v[120:123]
	v_mfma_f32_16x16x32_bf16 v[108:111], v[132:135], v[200:203], v[108:111]
	v_mfma_f32_16x16x32_bf16 v[104:107], v[140:143], v[200:203], v[104:107]
	v_mfma_f32_16x16x32_bf16 v[92:95], v[132:135], v[208:211], v[92:95]
	v_mfma_f32_16x16x32_bf16 v[88:91], v[140:143], v[208:211], v[88:91]
	v_mfma_f32_16x16x32_bf16 v[76:79], v[132:135], v[216:219], v[76:79]
	v_mfma_f32_16x16x32_bf16 v[72:75], v[140:143], v[216:219], v[72:75]
	v_mfma_f32_16x16x32_bf16 v[116:119], v[166:169], v[188:191], v[116:119]
	v_mfma_f32_16x16x32_bf16 v[112:115], v[180:183], v[188:191], v[112:115]
	v_mfma_f32_16x16x32_bf16 v[100:103], v[166:169], v[196:199], v[100:103]
	v_mfma_f32_16x16x32_bf16 v[96:99], v[180:183], v[196:199], v[96:99]
	v_mfma_f32_16x16x32_bf16 v[84:87], v[166:169], v[204:207], v[84:87]
	v_mfma_f32_16x16x32_bf16 v[80:83], v[180:183], v[204:207], v[80:83]
	v_mfma_f32_16x16x32_bf16 v[68:71], v[166:169], v[212:215], v[68:71]
	v_mfma_f32_16x16x32_bf16 v[64:67], v[180:183], v[212:215], v[64:67]
	v_mfma_f32_16x16x32_bf16 v[116:119], v[176:179], v[192:195], v[116:119]
	v_mfma_f32_16x16x32_bf16 v[112:115], v[184:187], v[192:195], v[112:115]
	v_mfma_f32_16x16x32_bf16 v[100:103], v[176:179], v[200:203], v[100:103]
	v_mfma_f32_16x16x32_bf16 v[96:99], v[184:187], v[200:203], v[96:99]
	v_mfma_f32_16x16x32_bf16 v[84:87], v[176:179], v[208:211], v[84:87]
	v_mfma_f32_16x16x32_bf16 v[80:83], v[184:187], v[208:211], v[80:83]
	v_mfma_f32_16x16x32_bf16 v[68:71], v[176:179], v[216:219], v[68:71]
	v_mfma_f32_16x16x32_bf16 v[64:67], v[184:187], v[216:219], v[64:67]
	s_barrier
	s_add_i32 s83, s83, s36
	v_lshl_add_u64 v[170:171], vcc, 0, v[150:151]
	s_mov_b32 m0, s83
	ds_read_b128 v[188:191], v242 offset:16384
	ds_read_b128 v[192:195], v242 offset:17408
	ds_read_b128 v[196:199], v242 offset:18432
	ds_read_b128 v[200:203], v242 offset:19456
	ds_read_b128 v[204:207], v242 offset:20480
	ds_read_b128 v[208:211], v242 offset:21504
	ds_read_b128 v[212:215], v242 offset:22528
	ds_read_b128 v[216:219], v242 offset:23552
	global_load_lds_dwordx4 v[170:171], off
	s_add_i32 m0, s83, 0x2000
	v_lshl_add_u64 v[232:233], vcc, 0, v[154:155]
	s_add_u32 vcc_lo, vcc_lo, s26
	s_addc_u32 vcc_hi, vcc_hi, 0
	s_add_i32 s82, s82, s36
	global_load_lds_dwordx4 v[232:233], off
	v_lshl_add_u64 v[234:235], vcc, 0, v[150:151]
	s_mov_b32 m0, s82
	v_lshl_add_u64 v[246:247], vcc, 0, v[154:155]
	global_load_lds_dwordx4 v[234:235], off
	s_add_i32 m0, s82, 0x2000
	v_lshl_add_u64 v[248:249], s[2:3], 0, v[148:149]
	global_load_lds_dwordx4 v[246:247], off
	s_mov_b32 m0, s37
	v_lshl_add_u64 v[250:251], s[2:3], 0, v[152:153]
	global_load_lds_dwordx4 v[248:249], off
	s_mov_b32 m0, s42
	s_nop 0
	global_load_lds_dwordx4 v[250:251], off
	s_waitcnt vmcnt(8) lgkmcnt(0)
	s_barrier
	v_mfma_f32_16x16x32_bf16 v[60:63], v[128:131], v[188:191], v[60:63]
	v_mfma_f32_16x16x32_bf16 v[56:59], v[136:139], v[188:191], v[56:59]
	v_mfma_f32_16x16x32_bf16 v[44:47], v[128:131], v[196:199], v[44:47]
	v_mfma_f32_16x16x32_bf16 v[40:43], v[136:139], v[196:199], v[40:43]
	v_mfma_f32_16x16x32_bf16 v[28:31], v[128:131], v[204:207], v[28:31]
	v_mfma_f32_16x16x32_bf16 v[24:27], v[136:139], v[204:207], v[24:27]
	v_mfma_f32_16x16x32_bf16 v[12:15], v[128:131], v[212:215], v[12:15]
	v_mfma_f32_16x16x32_bf16 v[8:11], v[136:139], v[212:215], v[8:11]
	v_mfma_f32_16x16x32_bf16 v[60:63], v[132:135], v[192:195], v[60:63]
	v_mfma_f32_16x16x32_bf16 v[56:59], v[140:143], v[192:195], v[56:59]
	v_mfma_f32_16x16x32_bf16 v[44:47], v[132:135], v[200:203], v[44:47]
	v_mfma_f32_16x16x32_bf16 v[40:43], v[140:143], v[200:203], v[40:43]
	v_mfma_f32_16x16x32_bf16 v[28:31], v[132:135], v[208:211], v[28:31]
	v_mfma_f32_16x16x32_bf16 v[24:27], v[140:143], v[208:211], v[24:27]
	v_mfma_f32_16x16x32_bf16 v[12:15], v[132:135], v[216:219], v[12:15]
	v_mfma_f32_16x16x32_bf16 v[8:11], v[140:143], v[216:219], v[8:11]
	v_mfma_f32_16x16x32_bf16 v[52:55], v[166:169], v[188:191], v[52:55]
	v_mfma_f32_16x16x32_bf16 v[48:51], v[180:183], v[188:191], v[48:51]
	v_mfma_f32_16x16x32_bf16 v[36:39], v[166:169], v[196:199], v[36:39]
	v_mfma_f32_16x16x32_bf16 v[32:35], v[180:183], v[196:199], v[32:35]
	v_mfma_f32_16x16x32_bf16 v[20:23], v[166:169], v[204:207], v[20:23]
	v_mfma_f32_16x16x32_bf16 v[16:19], v[180:183], v[204:207], v[16:19]
	v_mfma_f32_16x16x32_bf16 v[4:7], v[166:169], v[212:215], v[4:7]
	v_mfma_f32_16x16x32_bf16 v[0:3], v[180:183], v[212:215], v[0:3]
	v_mfma_f32_16x16x32_bf16 v[52:55], v[176:179], v[192:195], v[52:55]
	v_mfma_f32_16x16x32_bf16 v[48:51], v[184:187], v[192:195], v[48:51]
	v_mfma_f32_16x16x32_bf16 v[36:39], v[176:179], v[200:203], v[36:39]
	v_mfma_f32_16x16x32_bf16 v[32:35], v[184:187], v[200:203], v[32:35]
	v_mfma_f32_16x16x32_bf16 v[20:23], v[176:179], v[208:211], v[20:23]
	v_mfma_f32_16x16x32_bf16 v[16:19], v[184:187], v[208:211], v[16:19]
	v_mfma_f32_16x16x32_bf16 v[4:7], v[176:179], v[216:219], v[4:7]
	v_mfma_f32_16x16x32_bf16 v[0:3], v[184:187], v[216:219], v[0:3]
	s_barrier
	s_add_i32 s82, 0, 0x18000
	s_add_i32 s83, 0, 0x1c000
	v_add_u32_e32 v140, s82, v157
	v_add_u32_e32 v144, s83, v157
	ds_read_b128 v[128:131], v140
	ds_read_b128 v[132:135], v140 offset:1024
	ds_read_b128 v[136:139], v140 offset:2048
	ds_read_b128 v[140:143], v140 offset:3072
	ds_read_b128 v[166:169], v144
	ds_read_b128 v[176:179], v144 offset:1024
	ds_read_b128 v[180:183], v144 offset:2048
	ds_read_b128 v[184:187], v144 offset:3072
	s_add_u32 s2, s2, s58
	s_addc_u32 s3, s3, 0
	s_mov_b32 m0, s43
	v_lshl_add_u64 v[238:239], s[2:3], 0, v[148:149]
	ds_read_b128 v[188:191], v242 offset:32768
	ds_read_b128 v[192:195], v242 offset:33792
	ds_read_b128 v[196:199], v242 offset:34816
	ds_read_b128 v[200:203], v242 offset:35840
	ds_read_b128 v[204:207], v242 offset:36864
	ds_read_b128 v[208:211], v242 offset:37888
	ds_read_b128 v[212:215], v242 offset:38912
	ds_read_b128 v[216:219], v242 offset:39936
	global_load_lds_dwordx4 v[238:239], off
	v_lshl_add_u64 v[238:239], s[2:3], 0, v[152:153]
	s_mov_b32 m0, s16
	s_nop 0
	global_load_lds_dwordx4 v[238:239], off
	s_waitcnt vmcnt(8) lgkmcnt(0)
	s_barrier
	v_mfma_f32_16x16x32_bf16 v[124:127], v[128:131], v[188:191], v[124:127]
	v_mfma_f32_16x16x32_bf16 v[120:123], v[136:139], v[188:191], v[120:123]
	v_mfma_f32_16x16x32_bf16 v[108:111], v[128:131], v[196:199], v[108:111]
	v_mfma_f32_16x16x32_bf16 v[104:107], v[136:139], v[196:199], v[104:107]
	v_mfma_f32_16x16x32_bf16 v[92:95], v[128:131], v[204:207], v[92:95]
	v_mfma_f32_16x16x32_bf16 v[88:91], v[136:139], v[204:207], v[88:91]
	v_mfma_f32_16x16x32_bf16 v[76:79], v[128:131], v[212:215], v[76:79]
	v_mfma_f32_16x16x32_bf16 v[72:75], v[136:139], v[212:215], v[72:75]
	v_mfma_f32_16x16x32_bf16 v[124:127], v[132:135], v[192:195], v[124:127]
	v_mfma_f32_16x16x32_bf16 v[120:123], v[140:143], v[192:195], v[120:123]
	v_mfma_f32_16x16x32_bf16 v[108:111], v[132:135], v[200:203], v[108:111]
	v_mfma_f32_16x16x32_bf16 v[104:107], v[140:143], v[200:203], v[104:107]
	v_mfma_f32_16x16x32_bf16 v[92:95], v[132:135], v[208:211], v[92:95]
	v_mfma_f32_16x16x32_bf16 v[88:91], v[140:143], v[208:211], v[88:91]
	v_mfma_f32_16x16x32_bf16 v[76:79], v[132:135], v[216:219], v[76:79]
	v_mfma_f32_16x16x32_bf16 v[72:75], v[140:143], v[216:219], v[72:75]
	v_mfma_f32_16x16x32_bf16 v[116:119], v[166:169], v[188:191], v[116:119]
	v_mfma_f32_16x16x32_bf16 v[112:115], v[180:183], v[188:191], v[112:115]
	v_mfma_f32_16x16x32_bf16 v[100:103], v[166:169], v[196:199], v[100:103]
	v_mfma_f32_16x16x32_bf16 v[96:99], v[180:183], v[196:199], v[96:99]
	v_mfma_f32_16x16x32_bf16 v[84:87], v[166:169], v[204:207], v[84:87]
	v_mfma_f32_16x16x32_bf16 v[80:83], v[180:183], v[204:207], v[80:83]
	v_mfma_f32_16x16x32_bf16 v[68:71], v[166:169], v[212:215], v[68:71]
	v_mfma_f32_16x16x32_bf16 v[64:67], v[180:183], v[212:215], v[64:67]
	v_mfma_f32_16x16x32_bf16 v[116:119], v[176:179], v[192:195], v[116:119]
	v_mfma_f32_16x16x32_bf16 v[112:115], v[184:187], v[192:195], v[112:115]
	v_mfma_f32_16x16x32_bf16 v[100:103], v[176:179], v[200:203], v[100:103]
	v_mfma_f32_16x16x32_bf16 v[96:99], v[184:187], v[200:203], v[96:99]
	v_mfma_f32_16x16x32_bf16 v[84:87], v[176:179], v[208:211], v[84:87]
	v_mfma_f32_16x16x32_bf16 v[80:83], v[184:187], v[208:211], v[80:83]
	v_mfma_f32_16x16x32_bf16 v[68:71], v[176:179], v[216:219], v[68:71]
	v_mfma_f32_16x16x32_bf16 v[64:67], v[184:187], v[216:219], v[64:67]
	s_barrier
	s_add_i32 s2, s82, s36
	v_lshl_add_u64 v[170:171], v[170:171], 0, s[30:31]
	s_mov_b32 m0, s2
	ds_read_b128 v[188:191], v242 offset:49152
	ds_read_b128 v[192:195], v242 offset:50176
	ds_read_b128 v[196:199], v242 offset:51200
	ds_read_b128 v[200:203], v242 offset:52224
	ds_read_b128 v[204:207], v242 offset:53248
	ds_read_b128 v[208:211], v242 offset:54272
	ds_read_b128 v[212:215], v242 offset:55296
	ds_read_b128 v[216:219], v242 offset:56320
	global_load_lds_dwordx4 v[170:171], off
	v_lshl_add_u64 v[170:171], v[232:233], 0, s[30:31]
	s_add_i32 m0, s2, 0x2000
	s_add_i32 s2, s83, s36
	global_load_lds_dwordx4 v[170:171], off
	v_lshl_add_u64 v[170:171], v[234:235], 0, s[30:31]
	s_mov_b32 m0, s2
	s_nop 0
	global_load_lds_dwordx4 v[170:171], off
	v_lshl_add_u64 v[170:171], v[246:247], 0, s[30:31]
	s_add_i32 m0, s2, 0x2000
	s_nop 0
	global_load_lds_dwordx4 v[170:171], off
	v_lshl_add_u64 v[170:171], v[248:249], 0, s[30:31]
	s_mov_b32 m0, s63
	s_nop 0
	global_load_lds_dwordx4 v[170:171], off
	v_lshl_add_u64 v[170:171], v[250:251], 0, s[30:31]
	s_mov_b32 m0, s18
	s_nop 0
	global_load_lds_dwordx4 v[170:171], off
	s_waitcnt vmcnt(8) lgkmcnt(0)
	s_barrier
	v_mfma_f32_16x16x32_bf16 v[60:63], v[128:131], v[188:191], v[60:63]
	v_mfma_f32_16x16x32_bf16 v[56:59], v[136:139], v[188:191], v[56:59]
	v_mfma_f32_16x16x32_bf16 v[44:47], v[128:131], v[196:199], v[44:47]
	v_mfma_f32_16x16x32_bf16 v[40:43], v[136:139], v[196:199], v[40:43]
	v_mfma_f32_16x16x32_bf16 v[28:31], v[128:131], v[204:207], v[28:31]
	v_mfma_f32_16x16x32_bf16 v[24:27], v[136:139], v[204:207], v[24:27]
	v_mfma_f32_16x16x32_bf16 v[12:15], v[128:131], v[212:215], v[12:15]
	v_mfma_f32_16x16x32_bf16 v[8:11], v[136:139], v[212:215], v[8:11]
	v_mfma_f32_16x16x32_bf16 v[60:63], v[132:135], v[192:195], v[60:63]
	v_mfma_f32_16x16x32_bf16 v[56:59], v[140:143], v[192:195], v[56:59]
	v_mfma_f32_16x16x32_bf16 v[44:47], v[132:135], v[200:203], v[44:47]
	v_mfma_f32_16x16x32_bf16 v[40:43], v[140:143], v[200:203], v[40:43]
	v_mfma_f32_16x16x32_bf16 v[28:31], v[132:135], v[208:211], v[28:31]
	v_mfma_f32_16x16x32_bf16 v[24:27], v[140:143], v[208:211], v[24:27]
	v_mfma_f32_16x16x32_bf16 v[12:15], v[132:135], v[216:219], v[12:15]
	v_mfma_f32_16x16x32_bf16 v[8:11], v[140:143], v[216:219], v[8:11]
	v_mfma_f32_16x16x32_bf16 v[52:55], v[166:169], v[188:191], v[52:55]
	v_mfma_f32_16x16x32_bf16 v[48:51], v[180:183], v[188:191], v[48:51]
	v_mfma_f32_16x16x32_bf16 v[36:39], v[166:169], v[196:199], v[36:39]
	v_mfma_f32_16x16x32_bf16 v[32:35], v[180:183], v[196:199], v[32:35]
	v_mfma_f32_16x16x32_bf16 v[20:23], v[166:169], v[204:207], v[20:23]
	v_mfma_f32_16x16x32_bf16 v[16:19], v[180:183], v[204:207], v[16:19]
	v_mfma_f32_16x16x32_bf16 v[4:7], v[166:169], v[212:215], v[4:7]
	v_mfma_f32_16x16x32_bf16 v[0:3], v[180:183], v[212:215], v[0:3]
	v_mfma_f32_16x16x32_bf16 v[52:55], v[176:179], v[192:195], v[52:55]
	v_mfma_f32_16x16x32_bf16 v[48:51], v[184:187], v[192:195], v[48:51]
	v_mfma_f32_16x16x32_bf16 v[36:39], v[176:179], v[200:203], v[36:39]
	v_mfma_f32_16x16x32_bf16 v[32:35], v[184:187], v[200:203], v[32:35]
	v_mfma_f32_16x16x32_bf16 v[20:23], v[176:179], v[208:211], v[20:23]
	v_mfma_f32_16x16x32_bf16 v[16:19], v[184:187], v[208:211], v[16:19]
	v_mfma_f32_16x16x32_bf16 v[4:7], v[176:179], v[216:219], v[4:7]
	v_mfma_f32_16x16x32_bf16 v[0:3], v[184:187], v[216:219], v[0:3]
	s_barrier
	s_add_u32 s0, s0, 0x100
	s_addc_u32 s1, s1, 0
	s_add_u32 s11, s11, 0x100
	s_addc_u32 s24, s24, 0
	s_cmp_ge_u32 s90, s60
	s_mov_b32 s2, s90
	s_cbranch_scc0 .LBB0_295
	s_branch .LBB0_297
